# gdn_prep in-loop gate prefix scan via DPP row_shr/row_bcast instead of 7 dependent ds_bpermute (on top of v67)
# baseline (speedup 1.0000x reference)
; #define LAS __attribute__((address_space(3)))
; __device__ __forceinline__ void gdn_prep_all(const Params& P, LAS unsigned char* lds, int tid, int lane, int wave, int G) {
;     ...
;             const int b = lane >> 4, c = lane & 15;
;             float d[16];
; #pragma unroll
;             for (int i = 0; i < 16; ++i) {
;                 float a0 = (i == c) ? 1.f : 0.f;
; #pragma unroll
;                 for (int k = 0; k < (i + 3) / 4; ++k) { const f32x4 l4 = *(const LAS f32x4*)(hb + LM_OFF + (16 * b + i) * 272 + (16 * b + 4 * k) * 4);
; #pragma unroll
;                     for (int e = 0; e < 4; ++e) if (4 * k + e < i) a0 -= l4[e] * d[4 * k + e]; }
;                 d[i] = a0;
;             }
; #pragma unroll
;             for (int i = 0; i < 16; ++i) *(LAS float*)(hb + DI_OFF + ((b * 16 + i) * 16 + c) * 4) = d[i];
.LBB0_462:
	s_and_b64 vcc, exec, s[14:15]
	s_cbranch_vccz .LBB0_467
	ds_read_b128 v[32:35], v172 offset:37136
	s_waitcnt lgkmcnt(0)
	ds_read_b128 v[34:37], v172 offset:37408
	s_waitcnt lgkmcnt(0)
	ds_read_b128 v[36:39], v172 offset:37680
	ds_read_b128 v[40:43], v172 offset:37952
	s_andn2_b64 vcc, exec, s[92:93]
	v_fma_f32 v31, -v121, v32, v122
	v_fma_f32 v32, -v121, v34, v123
	v_fma_f32 v50, -v35, v31, v32
	s_waitcnt lgkmcnt(1)
	v_fma_f32 v32, -v121, v36, v124
	v_fma_f32 v32, -v37, v31, v32
	v_fma_f32 v51, -v38, v50, v32
	ds_read_b128 v[32:35], v172 offset:38224
	s_waitcnt lgkmcnt(1)
	v_fma_f32 v36, -v121, v40, v125
	v_fma_f32 v36, -v31, v41, v36
	v_fma_f32 v36, -v42, v50, v36
	v_fma_f32 v52, -v43, v51, v36
	ds_read_b128 v[36:39], v172 offset:38240
	s_waitcnt lgkmcnt(1)
	v_fma_f32 v32, -v121, v32, v126
	s_waitcnt lgkmcnt(0)
	ds_read_b128 v[38:41], v172 offset:38496
	v_fma_f32 v32, -v31, v33, v32
	v_fma_f32 v32, -v34, v50, v32
	v_fma_f32 v32, -v35, v51, v32
	v_fma_f32 v53, -v36, v52, v32
	ds_read_b128 v[32:35], v172 offset:38512
	s_waitcnt lgkmcnt(0)
	v_fma_f32 v34, -v121, v38, v127
	v_fma_f32 v34, -v31, v39, v34
	v_fma_f32 v38, -v50, v40, v34
	ds_read_b128 v[34:37], v172 offset:38768
	v_fma_f32 v38, -v41, v51, v38
	v_fma_f32 v32, -v32, v52, v38
	v_fma_f32 v54, -v33, v53, v32
	ds_read_b128 v[38:41], v172 offset:38784
	s_waitcnt lgkmcnt(1)
	v_fma_f32 v32, -v121, v34, v128
	v_fma_f32 v32, -v31, v35, v32
	v_fma_f32 v32, -v50, v36, v32
	v_fma_f32 v36, -v51, v37, v32
	ds_read_b128 v[32:35], v172 offset:39040
	s_waitcnt lgkmcnt(1)
	v_fma_f32 v36, -v52, v38, v36
	v_fma_f32 v36, -v39, v53, v36
	v_fma_f32 v55, -v40, v54, v36
	ds_read_b128 v[36:39], v172 offset:39056
	s_waitcnt lgkmcnt(1)
	v_fma_f32 v32, -v121, v32, v129
	v_fma_f32 v32, -v31, v33, v32
	v_fma_f32 v32, -v50, v34, v32
	v_fma_f32 v32, -v51, v35, v32
	s_waitcnt lgkmcnt(0)
	v_fma_f32 v36, -v52, v36, v32
	ds_read_b128 v[32:35], v172 offset:39312
	v_fma_f32 v36, -v53, v37, v36
	v_fma_f32 v36, -v38, v54, v36
	v_fma_f32 v56, -v39, v55, v36
	ds_read_b128 v[36:39], v172 offset:39328
	s_waitcnt lgkmcnt(1)
	v_fma_f32 v32, -v121, v32, v130
	v_fma_f32 v32, -v31, v33, v32
	v_fma_f32 v32, -v50, v34, v32
	v_fma_f32 v32, -v51, v35, v32
	s_waitcnt lgkmcnt(0)
	v_fma_f32 v36, -v52, v36, v32
	ds_read_b128 v[32:35], v172 offset:39344
	ds_read_b128 v[40:43], v172 offset:39584
	s_waitcnt lgkmcnt(1)
	v_fma_f32 v33, -v53, v37, v36
	v_fma_f32 v33, -v38, v54, v33
	v_fma_f32 v33, -v39, v55, v33
	v_fma_f32 v57, -v32, v56, v33
	ds_read_b128 v[32:35], v172 offset:39600
	s_waitcnt lgkmcnt(1)
	v_fma_f32 v36, -v121, v40, v131
	v_fma_f32 v36, -v31, v41, v36
	v_fma_f32 v36, -v50, v42, v36
	v_fma_f32 v40, -v51, v43, v36
	ds_read_b128 v[36:39], v172 offset:39616
	s_waitcnt lgkmcnt(1)
	v_fma_f32 v32, -v52, v32, v40
	v_fma_f32 v32, -v53, v33, v32
	s_waitcnt lgkmcnt(0)
	ds_read_b128 v[38:41], v172 offset:39856
	v_fma_f32 v32, -v54, v34, v32
	v_fma_f32 v32, -v35, v55, v32
	v_fma_f32 v32, -v36, v56, v32
	v_fma_f32 v58, -v37, v57, v32
	ds_read_b128 v[32:35], v172 offset:39872
	s_waitcnt lgkmcnt(1)
	v_fma_f32 v36, -v121, v38, v132
	v_fma_f32 v36, -v31, v39, v36
	v_fma_f32 v36, -v50, v40, v36
	v_fma_f32 v36, -v51, v41, v36
	s_waitcnt lgkmcnt(0)
	v_fma_f32 v32, -v52, v32, v36
	ds_read_b128 v[36:39], v172 offset:39888
	ds_read_b128 v[40:43], v172 offset:40128
	v_fma_f32 v32, -v53, v33, v32
	v_fma_f32 v32, -v54, v34, v32
	v_fma_f32 v32, -v55, v35, v32
	s_waitcnt lgkmcnt(1)
	v_fma_f32 v32, -v56, v36, v32
	v_fma_f32 v32, -v37, v57, v32
	v_fma_f32 v59, -v38, v58, v32
	ds_read_b128 v[32:35], v172 offset:40144
	s_waitcnt lgkmcnt(1)
	v_fma_f32 v36, -v121, v40, v133
	v_fma_f32 v36, -v31, v41, v36
	v_fma_f32 v36, -v50, v42, v36
	v_fma_f32 v40, -v51, v43, v36
	ds_read_b128 v[36:39], v172 offset:40160
	s_waitcnt lgkmcnt(1)
	v_fma_f32 v32, -v52, v32, v40
	v_fma_f32 v32, -v53, v33, v32
	v_fma_f32 v32, -v54, v34, v32
	v_fma_f32 v32, -v55, v35, v32
	s_waitcnt lgkmcnt(0)
	v_fma_f32 v36, -v56, v36, v32
	ds_read_b128 v[32:35], v172 offset:40400
	v_fma_f32 v36, -v57, v37, v36
	v_fma_f32 v36, -v38, v58, v36
	v_fma_f32 v60, -v39, v59, v36
	ds_read_b128 v[36:39], v172 offset:40416
	s_waitcnt lgkmcnt(1)
	v_fma_f32 v32, -v121, v32, v134
	v_fma_f32 v32, -v31, v33, v32
	v_fma_f32 v32, -v50, v34, v32
	v_fma_f32 v32, -v51, v35, v32
	s_waitcnt lgkmcnt(0)
	v_fma_f32 v36, -v52, v36, v32
	ds_read_b128 v[32:35], v172 offset:40432
	v_fma_f32 v36, -v53, v37, v36
	v_fma_f32 v36, -v54, v38, v36
	v_fma_f32 v40, -v55, v39, v36
	ds_read_b128 v[36:39], v172 offset:40448
	s_waitcnt lgkmcnt(1)
	v_fma_f32 v32, -v56, v32, v40
	s_waitcnt lgkmcnt(0)
	ds_read_b128 v[38:41], v172 offset:40672
	v_fma_f32 v32, -v57, v33, v32
	v_fma_f32 v32, -v34, v58, v32
	v_fma_f32 v32, -v35, v59, v32
	v_fma_f32 v61, -v36, v60, v32
	ds_read_b128 v[32:35], v172 offset:40688
	s_waitcnt lgkmcnt(1)
	v_fma_f32 v36, -v121, v38, v135
	v_fma_f32 v36, -v31, v39, v36
	v_fma_f32 v36, -v50, v40, v36
	v_fma_f32 v36, -v51, v41, v36
	s_waitcnt lgkmcnt(0)
	v_fma_f32 v32, -v52, v32, v36
	ds_read_b128 v[36:39], v172 offset:40704
	v_fma_f32 v32, -v53, v33, v32
	v_fma_f32 v32, -v54, v34, v32
	v_fma_f32 v40, -v55, v35, v32
	ds_read_b128 v[32:35], v172 offset:40720
	s_waitcnt lgkmcnt(0)
	v_fma_f32 v34, -v56, v36, v40
	v_fma_f32 v34, -v57, v37, v34
	v_fma_f32 v34, -v58, v38, v34
	v_fma_f32 v34, -v39, v59, v34
	v_fma_f32 v32, -v32, v60, v34
	ds_read_b128 v[34:37], v173 offset:36864
	v_fma_f32 v32, -v33, v61, v32
	ds_read_b128 v[38:41], v173 offset:36880
	ds_read_b128 v[42:45], v173 offset:36896
	ds_read_b128 v[46:49], v173 offset:36912
	s_waitcnt lgkmcnt(3)
	v_fma_f32 v33, -v121, v34, v136
	v_fma_f32 v33, -v31, v35, v33
	v_fma_f32 v33, -v50, v36, v33
	v_fma_f32 v33, -v51, v37, v33
	s_waitcnt lgkmcnt(2)
	v_fma_f32 v33, -v52, v38, v33
	v_fma_f32 v33, -v53, v39, v33
	v_fma_f32 v33, -v54, v40, v33
	v_fma_f32 v33, -v55, v41, v33
	s_waitcnt lgkmcnt(1)
	v_fma_f32 v33, -v56, v42, v33
	v_fma_f32 v33, -v57, v43, v33
	v_fma_f32 v33, -v58, v44, v33
	v_fma_f32 v33, -v59, v45, v33
	s_waitcnt lgkmcnt(0)
	v_fma_f32 v33, -v60, v46, v33
	v_fma_f32 v33, -v47, v61, v33
	v_add_u32_e32 v34, 0xd800, v174
	v_fma_f32 v33, -v48, v32, v33
	ds_write2_b32 v34, v121, v31 offset0:64 offset1:80
	ds_write2_b32 v34, v50, v51 offset0:96 offset1:112
	ds_write2_b32 v34, v52, v53 offset0:128 offset1:144
	ds_write2_b32 v34, v54, v55 offset0:160 offset1:176
	ds_write2_b32 v34, v56, v57 offset0:192 offset1:208
	ds_write2_b32 v34, v58, v59 offset0:224 offset1:240
	v_add_u32_e32 v31, 0xdc00, v174
	ds_write2_b32 v31, v60, v61 offset1:16
	ds_write_b32 v174, v32 offset:56448
	ds_write_b32 v175, v33 offset:55552
	s_cbranch_vccnz .LBB0_467
	s_waitcnt vmcnt(1)
	v_mov_b32_e32 v32, v107
	v_readlane_b32 s18, v247, 54
	v_readlane_b32 s19, v247, 55
	v_add_f32_dpp v32, v32, v32 row_shr:1 row_mask:0xf bank_mask:0xf
	s_nop 1
	v_add_f32_dpp v32, v32, v32 row_shr:2 row_mask:0xf bank_mask:0xf
	s_nop 1
	v_add_f32_dpp v32, v32, v32 row_shr:4 row_mask:0xf bank_mask:0xf
	s_nop 1
	v_add_f32_dpp v32, v32, v32 row_shr:8 row_mask:0xf bank_mask:0xf
	s_nop 1
	v_add_f32_dpp v32, v32, v32 row_bcast:15 row_mask:0xa bank_mask:0xf
	s_nop 1
	v_add_f32_dpp v32, v32, v32 row_bcast:31 row_mask:0xc bank_mask:0xf
	s_nop 1
	v_readlane_b32 s12, v32, 63
	s_nop 0
	v_mov_b32_e32 v31, s12
	v_mul_f32_e32 v33, 0x3fb8aa3b, v32
	v_exp_f32_e32 v33, v33
	s_and_b64 s[12:13], s[60:61], exec
	s_cselect_b32 s11, s4, s83
	s_waitcnt lgkmcnt(0)
	v_sub_f32_e32 v34, v31, v32
	v_mul_f32_e32 v34, 0x3fb8aa3b, v34
	v_exp_f32_e32 v34, v34
	v_lshl_add_u32 v35, v1, 2, s11
	s_waitcnt vmcnt(0)
	ds_write2st64_b32 v35, v32, v108 offset1:1
	v_mul_f32_e32 v32, v108, v33
	ds_write2st64_b32 v35, v33, v34 offset0:2 offset1:3
	ds_write_b32 v35, v32 offset:1024
	s_and_saveexec_b64 s[14:15], s[18:19]
	s_cbranch_execz .LBB0_466
	s_lshl_b32 s11, s2, 1
	s_and_b32 s12, s11, 6
	s_add_i32 s12, s12, s82
	s_and_b32 s11, s11, -8
	s_add_i32 s12, s12, s11
	v_mul_f32_e32 v31, 0x3fb8aa3b, v31
	s_ashr_i32 s13, s12, 31
	v_exp_f32_e32 v31, v31
	s_lshl_b64 s[12:13], s[12:13], 2
	s_add_u32 s12, s37, s12
	v_readlane_b32 s11, v247, 53
	s_addc_u32 s13, s11, s13
	global_store_dword v30, v31, s[12:13]
